# retention scan: the four V-slice fragment reads of each step issued together (own registers) instead of one before each dependent MFMA; no two-step K prefetch
# speedup vs baseline: 1.0030x; 1.0030x over previous
; #define LAS __attribute__((address_space(3)))
; DI void st_bf16x4(bf16_t* p, f32x4 v) { u32x2 w; w.x = cvt_pk_bf16(v[0], v[1]); w.y = cvt_pk_bf16(v[2], v[3]); *(u32x2*)p = w; }
; #define MFMA16(a, b, c) __builtin_amdgcn_mfma_f32_16x16x32_bf16((a), (b), (c), 0, 0, 0)
; DI void phase_ret_scan(const Params& p, int l, LAS unsigned char* lds) {
;     ...
;         for (int step = 0; step < 18; ++step) {
;             const int c = dir == 0 ? step : (step < 2 ? 1 - step : 19 - step);
;             const int sn = step < 17 ? step + 1 : 17;
;             const int cn = dir == 0 ? sn : (sn < 2 ? 1 - sn : 19 - sn);
;             bf16x8 na_[4];
; #pragma unroll
;             for (int ks = 0; ks < 4; ++ks) na_[ks] = *(const bf16x8*)(kt + cn * 128 + ks * 32);
;             st_bf16x4(sb + (size_t)c * 16384, st);
;             f32x4 u = (f32x4){0.f, 0.f, 0.f, 0.f};
; #pragma unroll
;             for (int ks = 0; ks < 4; ++ks) u = MFMA16(scale_bf16x8(ca[ks], wt[ks]), *(const LAS bf16x8*)(vl + (c * 128 + ks * 32) * 2), u);
;             st = st * gL + u;
; #pragma unroll
;             for (int ks = 0; ks < 4; ++ks) ca[ks] = na_[ks];
.LBB0_1084:
	s_cmp_eq_u32 s10, 0
	s_cselect_b32 s1, 1, 19
	s_add_i32 s1, s1, s10
	s_or_b32 s12, s0, 1
	s_add_i32 s13, s1, -1
	s_and_b64 s[6:7], vcc, exec
	s_cselect_b32 s6, s12, s13
	s_lshl_b32 s12, s6, 7
	s_waitcnt vmcnt(4)
	v_lshlrev_b32_e32 v40, 16, v0
	v_and_b32_e32 v0, 0xffff0000, v0
	v_lshlrev_b32_e32 v81, 16, v1
	v_and_b32_e32 v1, 0xffff0000, v1
	s_ashr_i32 s13, s12, 31
	v_lshlrev_b32_e32 v188, 16, v3
	s_waitcnt vmcnt(3)
	v_lshlrev_b32_e32 v189, 16, v12
	v_lshlrev_b32_e32 v190, 16, v13
	v_lshlrev_b32_e32 v191, 16, v14
	v_lshlrev_b32_e32 v192, 16, v15
	s_waitcnt vmcnt(2)
	v_lshlrev_b32_e32 v193, 16, v8
	v_lshlrev_b32_e32 v194, 16, v9
	v_lshlrev_b32_e32 v195, 16, v10
	v_lshlrev_b32_e32 v196, 16, v11
	s_waitcnt vmcnt(1)
	v_lshlrev_b32_e32 v197, 16, v4
	v_lshlrev_b32_e32 v198, 16, v5
	v_lshlrev_b32_e32 v199, 16, v6
	v_mul_f32_e32 v201, v27, v0
	v_mul_f32_e32 v203, v29, v1
	v_lshl_add_u64 v[0:1], s[12:13], 1, v[84:85]
	v_mul_f32_e32 v209, v32, v188
	v_mul_f32_e32 v211, v34, v189
	v_mul_f32_e32 v212, v83, v190
	v_mul_f32_e32 v213, v167, v191
	v_mul_f32_e32 v214, v169, v192
	v_mul_f32_e32 v215, v171, v193
	v_mul_f32_e32 v217, v173, v194
	v_mul_f32_e32 v219, v175, v195
	v_mul_f32_e32 v221, v177, v196
	v_mul_f32_e32 v223, v179, v197
	v_mul_f32_e32 v225, v181, v198
	v_mul_f32_e32 v227, v183, v199
	global_load_dwordx4 v[188:191], v[0:1], off
	global_load_dwordx4 v[192:195], v[0:1], off offset:64
	global_load_dwordx4 v[196:199], v[0:1], off offset:128
	s_and_b64 s[12:13], vcc, exec
	s_cselect_b32 s12, s0, s1
	s_ashr_i32 s13, s12, 31
	v_lshlrev_b32_e32 v187, 16, v2
	v_and_b32_e32 v2, 0xffff0000, v2
	v_and_b32_e32 v3, 0xffff0000, v3
	global_load_dwordx4 v[204:207], v[0:1], off offset:192
	v_lshl_add_u32 v231, s12, 8, v88
	ds_read_b128 v[234:237], v231
	ds_read_b128 v[238:241], v231 offset:64
	ds_read_b128 v[242:245], v231 offset:128
	ds_read_b128 v[246:249], v231 offset:192
	s_lshl_b64 s[12:13], s[12:13], 15
	v_and_b32_e32 v4, 0xffff0000, v4
	v_and_b32_e32 v5, 0xffff0000, v5
	v_and_b32_e32 v6, 0xffff0000, v6
	v_lshlrev_b32_e32 v200, 16, v7
	v_and_b32_e32 v7, 0xffff0000, v7
	v_mul_f32_e32 v208, v31, v2
	v_mul_f32_e32 v210, v33, v3
	v_cvt_pk_bf16_f32 v0, v22, v23
	v_cvt_pk_bf16_f32 v1, v24, v25
	v_lshl_add_u64 v[2:3], v[16:17], 0, s[12:13]
	v_mul_f32_e32 v40, v26, v40
	v_mul_f32_e32 v81, v28, v81
	v_mul_f32_e32 v187, v30, v187
	v_mul_f32_e32 v224, v180, v4
	v_mul_f32_e32 v226, v182, v5
	v_mul_f32_e32 v228, v184, v6
	v_mul_f32_e32 v229, v186, v7
	global_store_dwordx2 v[2:3], v[0:1], off
	v_cvt_pk_bf16_f32 v0, v40, v201
	v_cvt_pk_bf16_f32 v1, v81, v203
	v_cvt_pk_bf16_f32 v2, v187, v208
	v_cvt_pk_bf16_f32 v3, v209, v210
	v_and_b32_e32 v12, 0xffff0000, v12
	v_and_b32_e32 v13, 0xffff0000, v13
	v_and_b32_e32 v14, 0xffff0000, v14
	v_and_b32_e32 v15, 0xffff0000, v15
	s_add_i32 s1, s0, 2
	v_and_b32_e32 v8, 0xffff0000, v8
	v_and_b32_e32 v9, 0xffff0000, v9
	v_and_b32_e32 v10, 0xffff0000, v10
	v_and_b32_e32 v11, 0xffff0000, v11
	v_mul_f32_e32 v12, v35, v12
	v_mul_f32_e32 v13, v166, v13
	v_mul_f32_e32 v14, v168, v14
	v_mul_f32_e32 v15, v170, v15
	s_cmp_lg_u32 s0, 16
	v_mul_f32_e32 v216, v172, v8
	v_mul_f32_e32 v218, v174, v9
	v_mul_f32_e32 v220, v176, v10
	v_mul_f32_e32 v222, v178, v11
	v_cvt_pk_bf16_f32 v8, v211, v12
	v_cvt_pk_bf16_f32 v9, v212, v13
	v_cvt_pk_bf16_f32 v10, v213, v14
	v_cvt_pk_bf16_f32 v11, v214, v15
	s_cselect_b32 s0, s1, 17
	s_cmp_gt_u32 s0, 1
	s_waitcnt lgkmcnt(3)
	v_mfma_f32_16x16x32_bf16 v[0:3], v[0:3], v[234:237], 0
	s_cselect_b32 s7, 19, 1
	s_sub_i32 s7, s7, s0
	v_cvt_pk_bf16_f32 v208, v215, v216
	v_cvt_pk_bf16_f32 v209, v217, v218
	v_cvt_pk_bf16_f32 v210, v219, v220
	v_cvt_pk_bf16_f32 v211, v221, v222
	s_and_b64 s[12:13], vcc, exec
	s_cselect_b32 s0, s0, s7
	s_waitcnt lgkmcnt(2)
	v_mfma_f32_16x16x32_bf16 v[4:7], v[8:11], v[238:241], v[0:3]
	s_lshl_b32 s12, s0, 7
	s_ashr_i32 s13, s12, 31
	v_cvt_pk_bf16_f32 v216, v223, v224
	v_cvt_pk_bf16_f32 v217, v225, v226
	v_lshl_add_u64 v[224:225], s[12:13], 1, v[84:85]
	v_mul_f32_e32 v200, v185, v200
	v_cvt_pk_bf16_f32 v218, v227, v228
	v_cvt_pk_bf16_f32 v219, v200, v229
	global_load_dwordx4 v[0:3], v[224:225], off
	s_waitcnt lgkmcnt(1)
; #define LAS __attribute__((address_space(3)))
; DI void st_bf16x4(bf16_t* p, f32x4 v) { u32x2 w; w.x = cvt_pk_bf16(v[0], v[1]); w.y = cvt_pk_bf16(v[2], v[3]); *(u32x2*)p = w; }
; #define MFMA16(a, b, c) __builtin_amdgcn_mfma_f32_16x16x32_bf16((a), (b), (c), 0, 0, 0)
; DI void phase_ret_scan(const Params& p, int l, LAS unsigned char* lds) {
;     ...
;         for (int step = 0; step < 18; ++step) {
;             const int c = dir == 0 ? step : (step < 2 ? 1 - step : 19 - step);
;             const int sn = step < 17 ? step + 1 : 17;
;             const int cn = dir == 0 ? sn : (sn < 2 ? 1 - sn : 19 - sn);
;             bf16x8 na_[4];
; #pragma unroll
;             for (int ks = 0; ks < 4; ++ks) na_[ks] = *(const bf16x8*)(kt + cn * 128 + ks * 32);
;             st_bf16x4(sb + (size_t)c * 16384, st);
;             f32x4 u = (f32x4){0.f, 0.f, 0.f, 0.f};
; #pragma unroll
;             for (int ks = 0; ks < 4; ++ks) u = MFMA16(scale_bf16x8(ca[ks], wt[ks]), *(const LAS bf16x8*)(vl + (c * 128 + ks * 32) * 2), u);
;             st = st * gL + u;
; #pragma unroll
;             for (int ks = 0; ks < 4; ++ks) ca[ks] = na_[ks];
	v_mfma_f32_16x16x32_bf16 v[208:211], v[208:211], v[242:245], v[4:7]
	global_load_dwordx4 v[12:15], v[224:225], off offset:64
	global_load_dwordx4 v[8:11], v[224:225], off offset:128
	s_nop 0
	global_load_dwordx4 v[4:7], v[224:225], off offset:192
	s_ashr_i32 s7, s6, 31
	v_mov_b32_e32 v19, v18
	s_waitcnt lgkmcnt(0)
	v_mfma_f32_16x16x32_bf16 v[208:211], v[216:219], v[246:249], v[208:211]
	v_lshl_add_u32 v230, s6, 8, v88
	ds_read_b128 v[234:237], v230
	ds_read_b128 v[238:241], v230 offset:64
	ds_read_b128 v[242:245], v230 offset:128
	ds_read_b128 v[246:249], v230 offset:192
	s_lshl_b64 s[6:7], s[6:7], 15
	v_lshl_add_u64 v[200:201], v[16:17], 0, s[6:7]
	s_waitcnt vmcnt(8)
	v_lshlrev_b32_e32 v40, 16, v190
	v_and_b32_e32 v81, 0xffff0000, v190
	s_nop 1
	v_pk_fma_f32 v[212:213], v[18:19], v[24:25], v[210:211]
	v_pk_fma_f32 v[214:215], v[20:21], v[22:23], v[208:209]
	v_lshlrev_b32_e32 v24, 16, v189
	v_cvt_pk_bf16_f32 v22, v214, v215
	v_cvt_pk_bf16_f32 v23, v212, v213
	global_store_dwordx2 v[200:201], v[22:23], off
	v_lshlrev_b32_e32 v22, 16, v188
	v_and_b32_e32 v23, 0xffff0000, v188
	v_and_b32_e32 v25, 0xffff0000, v189
	v_and_b32_e32 v188, 0xffff0000, v191
	v_lshlrev_b32_e32 v187, 16, v191
	s_waitcnt vmcnt(8)
	v_lshlrev_b32_e32 v189, 16, v192
	v_and_b32_e32 v190, 0xffff0000, v192
	v_lshlrev_b32_e32 v191, 16, v193
	v_mul_f32_e32 v22, v26, v22
	v_mul_f32_e32 v23, v27, v23
	v_mul_f32_e32 v24, v28, v24
	v_mul_f32_e32 v25, v29, v25
	v_mul_f32_e32 v188, v33, v188
	v_mul_f32_e32 v40, v30, v40
	v_mul_f32_e32 v81, v31, v81
	v_mul_f32_e32 v187, v32, v187
	v_mul_f32_e32 v218, v34, v189
	v_mul_f32_e32 v219, v35, v190
	v_mul_f32_e32 v220, v83, v191
	v_cvt_pk_bf16_f32 v22, v22, v23
	v_cvt_pk_bf16_f32 v23, v24, v25
	v_cvt_pk_bf16_f32 v24, v40, v81
	v_cvt_pk_bf16_f32 v25, v187, v188
	v_and_b32_e32 v192, 0xffff0000, v193
	v_lshlrev_b32_e32 v193, 16, v194
	v_and_b32_e32 v194, 0xffff0000, v194
	v_lshlrev_b32_e32 v200, 16, v195
	v_and_b32_e32 v195, 0xffff0000, v195
	s_waitcnt vmcnt(7)
	v_lshlrev_b32_e32 v201, 16, v196
	v_and_b32_e32 v196, 0xffff0000, v196
	v_lshlrev_b32_e32 v203, 16, v197
	v_and_b32_e32 v197, 0xffff0000, v197
	v_lshlrev_b32_e32 v208, 16, v198
	v_and_b32_e32 v198, 0xffff0000, v198
	v_lshlrev_b32_e32 v209, 16, v199
	v_and_b32_e32 v199, 0xffff0000, v199
	v_mul_f32_e32 v194, v168, v194
	v_mul_f32_e32 v195, v170, v195
	v_mul_f32_e32 v221, v166, v192
	v_mul_f32_e32 v222, v167, v193
	v_mul_f32_e32 v200, v169, v200
	v_mul_f32_e32 v223, v172, v196
	v_mul_f32_e32 v224, v174, v197
	v_mul_f32_e32 v225, v176, v198
	v_mul_f32_e32 v226, v178, v199
	v_cvt_pk_bf16_f32 v192, v218, v219
	v_cvt_pk_bf16_f32 v193, v220, v221
	v_cvt_pk_bf16_f32 v194, v222, v194
	v_cvt_pk_bf16_f32 v195, v200, v195
	s_waitcnt lgkmcnt(3)
	v_mfma_f32_16x16x32_bf16 v[22:25], v[22:25], v[234:237], 0
	s_waitcnt vmcnt(6)
	v_lshlrev_b32_e32 v210, 16, v204
	v_and_b32_e32 v204, 0xffff0000, v204
	v_lshlrev_b32_e32 v211, 16, v205
	v_and_b32_e32 v205, 0xffff0000, v205
	v_lshlrev_b32_e32 v216, 16, v206
	v_and_b32_e32 v206, 0xffff0000, v206
	v_lshlrev_b32_e32 v217, 16, v207
	v_and_b32_e32 v207, 0xffff0000, v207
	v_mul_f32_e32 v201, v171, v201
	v_mul_f32_e32 v203, v173, v203
	v_mul_f32_e32 v208, v175, v208
	v_mul_f32_e32 v209, v177, v209
	v_mul_f32_e32 v227, v180, v204
	v_mul_f32_e32 v228, v182, v205
	v_mul_f32_e32 v229, v184, v206
	v_mul_f32_e32 v231, v186, v207
	v_cvt_pk_bf16_f32 v204, v201, v223
	v_cvt_pk_bf16_f32 v205, v203, v224
	v_cvt_pk_bf16_f32 v206, v208, v225
	v_cvt_pk_bf16_f32 v207, v209, v226
	s_waitcnt lgkmcnt(2)
	v_mfma_f32_16x16x32_bf16 v[22:25], v[192:195], v[238:241], v[22:25]
	v_mul_f32_e32 v210, v179, v210
	v_mul_f32_e32 v211, v181, v211
	v_mul_f32_e32 v216, v183, v216
	v_mul_f32_e32 v217, v185, v217
	v_cvt_pk_bf16_f32 v208, v210, v227
	v_cvt_pk_bf16_f32 v209, v211, v228
	v_cvt_pk_bf16_f32 v210, v216, v229
	v_cvt_pk_bf16_f32 v211, v217, v231
	s_waitcnt lgkmcnt(1)
	v_mfma_f32_16x16x32_bf16 v[22:25], v[204:207], v[242:245], v[22:25]
	s_add_i32 s10, s10, -2
	s_mov_b32 s0, s1
	s_waitcnt lgkmcnt(0)
	v_mfma_f32_16x16x32_bf16 v[22:25], v[208:211], v[246:249], v[22:25]
	s_cmp_eq_u32 s1, 18
	s_nop 6
	v_pk_fma_f32 v[24:25], v[18:19], v[212:213], v[24:25]
	v_pk_fma_f32 v[22:23], v[20:21], v[214:215], v[22:23]
	s_cbranch_scc0 .LBB0_1084
	s_mov_b64 s[0:1], 0
	s_branch .LBB0_1077

; #define LAS __attribute__((address_space(3)))
; DI void st_bf16x4(bf16_t* p, f32x4 v) { u32x2 w; w.x = cvt_pk_bf16(v[0], v[1]); w.y = cvt_pk_bf16(v[2], v[3]); *(u32x2*)p = w; }
; #define MFMA16(a, b, c) __builtin_amdgcn_mfma_f32_16x16x32_bf16((a), (b), (c), 0, 0, 0)
; DI void phase_ret_scan(const Params& p, int l, LAS unsigned char* lds) {
;     ...
;         for (int step = 0; step < 18; ++step) {
;             const int c = dir == 0 ? step : (step < 2 ? 1 - step : 19 - step);
;             const int sn = step < 17 ? step + 1 : 17;
;             const int cn = dir == 0 ? sn : (sn < 2 ? 1 - sn : 19 - sn);
;             bf16x8 na_[4];
; #pragma unroll
;             for (int ks = 0; ks < 4; ++ks) na_[ks] = *(const bf16x8*)(kt + cn * 128 + ks * 32);
;             st_bf16x4(sb + (size_t)c * 16384, st);
;             f32x4 u = (f32x4){0.f, 0.f, 0.f, 0.f};
; #pragma unroll
;             for (int ks = 0; ks < 4; ++ks) u = MFMA16(scale_bf16x8(ca[ks], wt[ks]), *(const LAS bf16x8*)(vl + (c * 128 + ks * 32) * 2), u);
;             st = st * gL + u;
; #pragma unroll
;             for (int ks = 0; ks < 4; ++ks) ca[ks] = na_[ks];
.LBB0_2531:
	s_cmp_eq_u32 s8, 0
	s_cselect_b32 s1, 1, 19
	s_add_i32 s1, s1, s8
	s_or_b32 s10, s0, 1
	s_add_i32 s11, s1, -1
	s_and_b64 s[2:3], vcc, exec
	s_cselect_b32 s2, s10, s11
	s_lshl_b32 s10, s2, 7
	s_waitcnt vmcnt(4)
	v_lshlrev_b32_e32 v40, 16, v0
	v_and_b32_e32 v0, 0xffff0000, v0
	v_lshlrev_b32_e32 v81, 16, v1
	v_and_b32_e32 v1, 0xffff0000, v1
	s_ashr_i32 s11, s10, 31
	v_lshlrev_b32_e32 v188, 16, v3
	s_waitcnt vmcnt(3)
	v_lshlrev_b32_e32 v189, 16, v12
	v_lshlrev_b32_e32 v190, 16, v13
	v_lshlrev_b32_e32 v191, 16, v14
	v_lshlrev_b32_e32 v192, 16, v15
	s_waitcnt vmcnt(2)
	v_lshlrev_b32_e32 v193, 16, v8
	v_lshlrev_b32_e32 v194, 16, v9
	v_lshlrev_b32_e32 v195, 16, v10
	v_lshlrev_b32_e32 v196, 16, v11
	s_waitcnt vmcnt(1)
	v_lshlrev_b32_e32 v197, 16, v4
	v_lshlrev_b32_e32 v198, 16, v5
	v_lshlrev_b32_e32 v199, 16, v6
	v_mul_f32_e32 v201, v27, v0
	v_mul_f32_e32 v208, v29, v1
	v_lshl_add_u64 v[0:1], s[10:11], 1, v[84:85]
	v_mul_f32_e32 v210, v32, v188
	v_mul_f32_e32 v212, v34, v189
	v_mul_f32_e32 v213, v83, v190
	v_mul_f32_e32 v214, v167, v191
	v_mul_f32_e32 v215, v169, v192
	v_mul_f32_e32 v216, v171, v193
	v_mul_f32_e32 v218, v173, v194
	v_mul_f32_e32 v220, v175, v195
	v_mul_f32_e32 v222, v177, v196
	v_mul_f32_e32 v224, v179, v197
	v_mul_f32_e32 v226, v181, v198
	v_mul_f32_e32 v228, v183, v199
	global_load_dwordx4 v[188:191], v[0:1], off
	global_load_dwordx4 v[192:195], v[0:1], off offset:64
	global_load_dwordx4 v[196:199], v[0:1], off offset:128
	s_and_b64 s[10:11], vcc, exec
	s_cselect_b32 s10, s0, s1
	s_ashr_i32 s11, s10, 31
	v_lshlrev_b32_e32 v187, 16, v2
	v_and_b32_e32 v2, 0xffff0000, v2
	v_and_b32_e32 v3, 0xffff0000, v3
	global_load_dwordx4 v[204:207], v[0:1], off offset:192
	v_lshl_add_u32 v232, s10, 8, v88
	ds_read_b128 v[234:237], v232
	ds_read_b128 v[238:241], v232 offset:64
	ds_read_b128 v[242:245], v232 offset:128
	ds_read_b128 v[246:249], v232 offset:192
	s_lshl_b64 s[10:11], s[10:11], 15
	v_and_b32_e32 v4, 0xffff0000, v4
	v_and_b32_e32 v5, 0xffff0000, v5
	v_and_b32_e32 v6, 0xffff0000, v6
	v_lshlrev_b32_e32 v200, 16, v7
	v_and_b32_e32 v7, 0xffff0000, v7
	v_mul_f32_e32 v209, v31, v2
	v_mul_f32_e32 v211, v33, v3
	v_cvt_pk_bf16_f32 v0, v22, v23
	v_cvt_pk_bf16_f32 v1, v24, v25
	v_lshl_add_u64 v[2:3], v[16:17], 0, s[10:11]
	v_mul_f32_e32 v40, v26, v40
	v_mul_f32_e32 v81, v28, v81
	v_mul_f32_e32 v187, v30, v187
	v_mul_f32_e32 v225, v180, v4
	v_mul_f32_e32 v227, v182, v5
	v_mul_f32_e32 v229, v184, v6
	v_mul_f32_e32 v230, v186, v7
	global_store_dwordx2 v[2:3], v[0:1], off
	v_cvt_pk_bf16_f32 v0, v40, v201
	v_cvt_pk_bf16_f32 v1, v81, v208
	v_cvt_pk_bf16_f32 v2, v187, v209
	v_cvt_pk_bf16_f32 v3, v210, v211
	v_and_b32_e32 v12, 0xffff0000, v12
	v_and_b32_e32 v13, 0xffff0000, v13
	v_and_b32_e32 v14, 0xffff0000, v14
	v_and_b32_e32 v15, 0xffff0000, v15
	s_add_i32 s1, s0, 2
	v_and_b32_e32 v8, 0xffff0000, v8
	v_and_b32_e32 v9, 0xffff0000, v9
	v_and_b32_e32 v10, 0xffff0000, v10
	v_and_b32_e32 v11, 0xffff0000, v11
	v_mul_f32_e32 v12, v35, v12
	v_mul_f32_e32 v13, v166, v13
	v_mul_f32_e32 v14, v168, v14
	v_mul_f32_e32 v15, v170, v15
	s_cmp_lg_u32 s0, 16
	v_mul_f32_e32 v217, v172, v8
	v_mul_f32_e32 v219, v174, v9
	v_mul_f32_e32 v221, v176, v10
	v_mul_f32_e32 v223, v178, v11
	v_cvt_pk_bf16_f32 v8, v212, v12
	v_cvt_pk_bf16_f32 v9, v213, v13
	v_cvt_pk_bf16_f32 v10, v214, v14
	v_cvt_pk_bf16_f32 v11, v215, v15
	s_cselect_b32 s0, s1, 17
	s_cmp_gt_u32 s0, 1
	s_waitcnt lgkmcnt(3)
	v_mfma_f32_16x16x32_bf16 v[0:3], v[0:3], v[234:237], 0
	s_cselect_b32 s3, 19, 1
	s_sub_i32 s3, s3, s0
	v_cvt_pk_bf16_f32 v208, v216, v217
	v_cvt_pk_bf16_f32 v209, v218, v219
	v_cvt_pk_bf16_f32 v210, v220, v221
	v_cvt_pk_bf16_f32 v211, v222, v223
	s_and_b64 s[10:11], vcc, exec
	s_cselect_b32 s0, s0, s3
	s_waitcnt lgkmcnt(2)
	v_mfma_f32_16x16x32_bf16 v[4:7], v[8:11], v[238:241], v[0:3]
	s_lshl_b32 s10, s0, 7
	s_ashr_i32 s11, s10, 31
	v_cvt_pk_bf16_f32 v216, v224, v225
	v_lshl_add_u64 v[224:225], s[10:11], 1, v[84:85]
	v_mul_f32_e32 v200, v185, v200
	v_cvt_pk_bf16_f32 v217, v226, v227
	v_cvt_pk_bf16_f32 v218, v228, v229
	v_cvt_pk_bf16_f32 v219, v200, v230
	global_load_dwordx4 v[0:3], v[224:225], off
	s_waitcnt lgkmcnt(1)
; #define LAS __attribute__((address_space(3)))
; DI void st_bf16x4(bf16_t* p, f32x4 v) { u32x2 w; w.x = cvt_pk_bf16(v[0], v[1]); w.y = cvt_pk_bf16(v[2], v[3]); *(u32x2*)p = w; }
; #define MFMA16(a, b, c) __builtin_amdgcn_mfma_f32_16x16x32_bf16((a), (b), (c), 0, 0, 0)
; DI void phase_ret_scan(const Params& p, int l, LAS unsigned char* lds) {
;     ...
;         for (int step = 0; step < 18; ++step) {
;             const int c = dir == 0 ? step : (step < 2 ? 1 - step : 19 - step);
;             const int sn = step < 17 ? step + 1 : 17;
;             const int cn = dir == 0 ? sn : (sn < 2 ? 1 - sn : 19 - sn);
;             bf16x8 na_[4];
; #pragma unroll
;             for (int ks = 0; ks < 4; ++ks) na_[ks] = *(const bf16x8*)(kt + cn * 128 + ks * 32);
;             st_bf16x4(sb + (size_t)c * 16384, st);
;             f32x4 u = (f32x4){0.f, 0.f, 0.f, 0.f};
; #pragma unroll
;             for (int ks = 0; ks < 4; ++ks) u = MFMA16(scale_bf16x8(ca[ks], wt[ks]), *(const LAS bf16x8*)(vl + (c * 128 + ks * 32) * 2), u);
;             st = st * gL + u;
; #pragma unroll
;             for (int ks = 0; ks < 4; ++ks) ca[ks] = na_[ks];
	v_mfma_f32_16x16x32_bf16 v[208:211], v[208:211], v[242:245], v[4:7]
	global_load_dwordx4 v[12:15], v[224:225], off offset:64
	global_load_dwordx4 v[8:11], v[224:225], off offset:128
	s_nop 0
	global_load_dwordx4 v[4:7], v[224:225], off offset:192
	s_ashr_i32 s3, s2, 31
	v_mov_b32_e32 v19, v18
	s_waitcnt lgkmcnt(0)
	v_mfma_f32_16x16x32_bf16 v[208:211], v[216:219], v[246:249], v[208:211]
	v_lshl_add_u32 v231, s2, 8, v88
	ds_read_b128 v[234:237], v231
	ds_read_b128 v[238:241], v231 offset:64
	ds_read_b128 v[242:245], v231 offset:128
	ds_read_b128 v[246:249], v231 offset:192
	s_lshl_b64 s[2:3], s[2:3], 15
	v_lshl_add_u64 v[200:201], v[16:17], 0, s[2:3]
	s_waitcnt vmcnt(8)
	v_lshlrev_b32_e32 v40, 16, v190
	v_and_b32_e32 v81, 0xffff0000, v190
	s_nop 1
	v_pk_fma_f32 v[212:213], v[18:19], v[24:25], v[210:211]
	v_pk_fma_f32 v[214:215], v[20:21], v[22:23], v[208:209]
	v_lshlrev_b32_e32 v24, 16, v189
	v_cvt_pk_bf16_f32 v22, v214, v215
	v_cvt_pk_bf16_f32 v23, v212, v213
	global_store_dwordx2 v[200:201], v[22:23], off
	v_lshlrev_b32_e32 v22, 16, v188
	v_and_b32_e32 v23, 0xffff0000, v188
	v_and_b32_e32 v25, 0xffff0000, v189
	v_and_b32_e32 v188, 0xffff0000, v191
	v_lshlrev_b32_e32 v187, 16, v191
	s_waitcnt vmcnt(8)
	v_lshlrev_b32_e32 v189, 16, v192
	v_and_b32_e32 v190, 0xffff0000, v192
	v_lshlrev_b32_e32 v191, 16, v193
	v_mul_f32_e32 v22, v26, v22
	v_mul_f32_e32 v23, v27, v23
	v_mul_f32_e32 v24, v28, v24
	v_mul_f32_e32 v25, v29, v25
	v_mul_f32_e32 v188, v33, v188
	v_mul_f32_e32 v40, v30, v40
	v_mul_f32_e32 v81, v31, v81
	v_mul_f32_e32 v187, v32, v187
	v_mul_f32_e32 v219, v34, v189
	v_mul_f32_e32 v220, v35, v190
	v_mul_f32_e32 v221, v83, v191
	v_cvt_pk_bf16_f32 v22, v22, v23
	v_cvt_pk_bf16_f32 v23, v24, v25
	v_cvt_pk_bf16_f32 v24, v40, v81
	v_cvt_pk_bf16_f32 v25, v187, v188
	v_and_b32_e32 v192, 0xffff0000, v193
	v_lshlrev_b32_e32 v193, 16, v194
	v_and_b32_e32 v194, 0xffff0000, v194
	v_lshlrev_b32_e32 v200, 16, v195
	v_and_b32_e32 v195, 0xffff0000, v195
	s_waitcnt vmcnt(7)
	v_lshlrev_b32_e32 v201, 16, v196
	v_and_b32_e32 v196, 0xffff0000, v196
	v_lshlrev_b32_e32 v208, 16, v197
	v_and_b32_e32 v197, 0xffff0000, v197
	v_lshlrev_b32_e32 v209, 16, v198
	v_and_b32_e32 v198, 0xffff0000, v198
	v_lshlrev_b32_e32 v210, 16, v199
	v_and_b32_e32 v199, 0xffff0000, v199
	v_mul_f32_e32 v194, v168, v194
	v_mul_f32_e32 v195, v170, v195
	v_mul_f32_e32 v222, v166, v192
	v_mul_f32_e32 v223, v167, v193
	v_mul_f32_e32 v200, v169, v200
	v_mul_f32_e32 v224, v172, v196
	v_mul_f32_e32 v225, v174, v197
	v_mul_f32_e32 v226, v176, v198
	v_mul_f32_e32 v227, v178, v199
	v_cvt_pk_bf16_f32 v192, v219, v220
	v_cvt_pk_bf16_f32 v193, v221, v222
	v_cvt_pk_bf16_f32 v194, v223, v194
	v_cvt_pk_bf16_f32 v195, v200, v195
	s_waitcnt lgkmcnt(3)
	v_mfma_f32_16x16x32_bf16 v[22:25], v[22:25], v[234:237], 0
	s_waitcnt vmcnt(6)
	v_lshlrev_b32_e32 v211, 16, v204
	v_and_b32_e32 v204, 0xffff0000, v204
	v_lshlrev_b32_e32 v216, 16, v205
	v_and_b32_e32 v205, 0xffff0000, v205
	v_lshlrev_b32_e32 v217, 16, v206
	v_and_b32_e32 v206, 0xffff0000, v206
	v_lshlrev_b32_e32 v218, 16, v207
	v_and_b32_e32 v207, 0xffff0000, v207
	v_mul_f32_e32 v201, v171, v201
	v_mul_f32_e32 v208, v173, v208
	v_mul_f32_e32 v209, v175, v209
	v_mul_f32_e32 v210, v177, v210
	v_mul_f32_e32 v228, v180, v204
	v_mul_f32_e32 v229, v182, v205
	v_mul_f32_e32 v230, v184, v206
	v_mul_f32_e32 v232, v186, v207
	v_cvt_pk_bf16_f32 v204, v201, v224
	v_cvt_pk_bf16_f32 v205, v208, v225
	v_cvt_pk_bf16_f32 v206, v209, v226
	v_cvt_pk_bf16_f32 v207, v210, v227
	s_waitcnt lgkmcnt(2)
	v_mfma_f32_16x16x32_bf16 v[22:25], v[192:195], v[238:241], v[22:25]
	v_mul_f32_e32 v211, v179, v211
	v_mul_f32_e32 v216, v181, v216
	v_mul_f32_e32 v217, v183, v217
	v_mul_f32_e32 v218, v185, v218
	v_cvt_pk_bf16_f32 v208, v211, v228
	v_cvt_pk_bf16_f32 v209, v216, v229
	v_cvt_pk_bf16_f32 v210, v217, v230
	v_cvt_pk_bf16_f32 v211, v218, v232
	s_waitcnt lgkmcnt(1)
	v_mfma_f32_16x16x32_bf16 v[22:25], v[204:207], v[242:245], v[22:25]
	s_add_i32 s8, s8, -2
	s_mov_b32 s0, s1
	s_waitcnt lgkmcnt(0)
	v_mfma_f32_16x16x32_bf16 v[22:25], v[208:211], v[246:249], v[22:25]
	s_cmp_eq_u32 s1, 18
	s_nop 6
	v_pk_fma_f32 v[24:25], v[18:19], v[212:213], v[24:25]
	v_pk_fma_f32 v[22:23], v[20:21], v[214:215], v[22:23]
	s_cbranch_scc0 .LBB0_2531
	s_mov_b64 s[0:1], 0
	s_branch .LBB0_2524
